# v035 + the last throw-away GU K-loop DMA address in saddr form (25 sites total)
# speedup vs baseline: 1.0038x; 1.0038x over previous
; #define PG8_STAGE(bufoff, gbase, voff) do { _Pragma("unroll") for (int _i = 0; _i < 2; ++_i) \
;         __builtin_amdgcn_global_load_lds((const unsigned*)((const char*)(gbase) + (voff)[_i]), (LAS unsigned*)(lds + (bufoff) + ldsw + _i * 8192), 16, 0, 0); } while (0)
; #define PG8_LDA(dst, b, h) do { _Pragma("unroll") for (int m = 0; m < 4; ++m) _Pragma("unroll") for (int k = 0; k < 2; ++k) dst[m][k] = *(const LAS bf16x8*)(lds + PG8_SA(b, h) + aoff + m * 2048 + k * 1024); } while (0)
; #define PG8_LDB(dst, b, h) do { _Pragma("unroll") for (int n = 0; n < 2; ++n) _Pragma("unroll") for (int k = 0; k < 2; ++k) dst[n][k] = *(const LAS bf16x8*)(lds + PG8_SB(b, h) + boff + n * 2048 + k * 1024); } while (0)
; #define PG8_MMA(ai, bj, At, Bt) do { __builtin_amdgcn_s_setprio(1); _Pragma("unroll") for (int m = 0; m < 4; ++m) _Pragma("unroll") for (int n = 0; n < 2; ++n) _Pragma("unroll") for (int k = 0; k < 2; ++k) \
;         acc[ai][bj][m][n] = __builtin_amdgcn_mfma_f32_16x16x32_bf16(Bt[n][k], At[m][k], acc[ai][bj][m][n], 0, 0, 0); __builtin_amdgcn_s_setprio(0); } while (0)
; #define PG8_WAIT_V(n) asm volatile("s_waitcnt vmcnt(" #n ")" ::: "memory")
; #define PG8_WAIT_L(n) asm volatile("s_waitcnt lgkmcnt(" #n ")" ::: "memory")
; #define PG8_BAR __builtin_amdgcn_s_barrier()
; #define PG8_SCHED __builtin_amdgcn_sched_barrier(0)
; template <class Epi, bool ALIGN_EPI>
; __device__ __forceinline__ void gemm_phase(LAS unsigned char* lds, const Gemm g, const StaticOrder& S, const Epi& E, const int wave_s) {
;     ...
;         for (int t = 0; t < nt; t += 2) {
;             const bool last = (t == nt - 2);
;             const char* a1 = cA + (size_t)(t + 1) * kstep;
;             const char* a2 = last ? nA : cA + (size_t)(t + 2) * kstep; const char* b2 = last ? nB : cB + (size_t)(t + 2) * kstep;
;             const char* a3 = a2 + kstep; const char* b3 = b2 + kstep;
;             PG8_LDB(B0, 0, 0); PG8_LDB(B1, 0, 1); PG8_SCHED; PG8_LDA(At, 0, 0); PG8_STAGE(PG8_SA(1, 1), a1 + hstepA, voffA);
;             PG8_WAIT_V(8); PG8_WAIT_L(0); PG8_BAR; PG8_MMA(0, 0, At, B0); PG8_MMA(0, 1, At, B1); PG8_BAR; PG8_SCHED;
;             PG8_LDA(At, 0, 1); PG8_STAGE(PG8_SB(0, 0), b2, voffB); PG8_STAGE(PG8_SB(0, 1), b2 + hstepB, voffB); PG8_STAGE(PG8_SA(0, 0), a2, voffA);
;             PG8_WAIT_V(8); PG8_WAIT_L(0); PG8_BAR; PG8_MMA(1, 0, At, B0); PG8_MMA(1, 1, At, B1); PG8_BAR; PG8_SCHED;
.LBB0_180:
	s_add_i32 s40, s38, 2
	s_add_u32 s41, s0, 0x80
	s_addc_u32 s39, s1, 0
	s_add_i32 s45, 0, 0x10000
	s_cmp_eq_u32 s93, s38
	s_cselect_b32 s39, s69, s39
	s_cselect_b32 s38, s68, s41
	v_add_u32_e32 v20, s45, v212
	s_cselect_b32 s49, s71, s44
	s_cselect_b32 s48, s70, s43
	s_add_i32 s41, 0, 0x14000
	ds_read_b128 v[96:99], v20
	ds_read_b128 v[100:103], v20 offset:1024
	ds_read_b128 v[104:107], v20 offset:2048
	ds_read_b128 v[140:143], v20 offset:3072
	v_add_u32_e32 v20, s41, v212
	ds_read_b128 v[152:155], v20
	ds_read_b128 v[156:159], v20 offset:1024
	ds_read_b128 v[170:173], v20 offset:2048
	ds_read_b128 v[174:177], v20 offset:3072
	s_add_i32 m0, s82, 0xc000
	ds_read_b128 v[178:181], v213
	ds_read_b128 v[188:191], v213 offset:1024
	ds_read_b128 v[192:195], v213 offset:2048
	ds_read_b128 v[196:199], v213 offset:3072
	ds_read_b128 v[200:203], v213 offset:4096
	ds_read_b128 v[204:207], v213 offset:5120
	ds_read_b128 v[214:217], v213 offset:6144
	ds_read_b128 v[218:221], v213 offset:7168
	global_load_lds_dwordx4 v168, s[0:1]
	s_add_i32 m0, s82, 0xe000
	s_nop 0
	global_load_lds_dwordx4 v166, s[0:1]
	s_waitcnt vmcnt(8)
	s_waitcnt lgkmcnt(0)
	s_barrier
	s_setprio 1
	s_waitcnt lgkmcnt(0)
	v_mfma_f32_16x16x32_bf16 v[148:151], v[96:99], v[178:181], v[148:151]
	v_mfma_f32_16x16x32_bf16 v[52:55], v[104:107], v[178:181], v[54:57]
	v_mfma_f32_16x16x32_bf16 v[144:147], v[96:99], v[192:195], v[144:147]
	v_mfma_f32_16x16x32_bf16 v[66:69], v[104:107], v[192:195], v[66:69]
	v_mfma_f32_16x16x32_bf16 v[132:135], v[96:99], v[200:203], v[132:135]
	v_mfma_f32_16x16x32_bf16 v[56:59], v[104:107], v[200:203], v[58:61]
	v_mfma_f32_16x16x32_bf16 v[124:127], v[96:99], v[214:217], v[124:127]
	v_mfma_f32_16x16x32_bf16 v[42:45], v[104:107], v[214:217], v[44:47]
	v_mfma_f32_16x16x32_bf16 v[148:151], v[100:103], v[188:191], v[148:151]
	v_mfma_f32_16x16x32_bf16 v[52:55], v[140:143], v[188:191], v[52:55]
	v_mfma_f32_16x16x32_bf16 v[144:147], v[100:103], v[196:199], v[144:147]
	v_mfma_f32_16x16x32_bf16 v[66:69], v[140:143], v[196:199], v[66:69]
	v_mfma_f32_16x16x32_bf16 v[132:135], v[100:103], v[204:207], v[132:135]
	v_mfma_f32_16x16x32_bf16 v[58:61], v[140:143], v[204:207], v[56:59]
	v_mfma_f32_16x16x32_bf16 v[124:127], v[100:103], v[218:221], v[124:127]
	v_mfma_f32_16x16x32_bf16 v[42:45], v[140:143], v[218:221], v[42:45]
	s_setprio 0
	s_setprio 1
	v_mfma_f32_16x16x32_bf16 v[136:139], v[152:155], v[178:181], v[136:139]
	v_mfma_f32_16x16x32_bf16 v[62:65], v[170:173], v[178:181], v[62:65]
	v_mfma_f32_16x16x32_bf16 v[128:131], v[152:155], v[192:195], v[128:131]
	v_mfma_f32_16x16x32_bf16 v[46:49], v[170:173], v[192:195], v[48:51]
	v_mfma_f32_16x16x32_bf16 v[120:123], v[152:155], v[200:203], v[120:123]
	v_mfma_f32_16x16x32_bf16 v[38:41], v[170:173], v[200:203], v[38:41]
	v_mfma_f32_16x16x32_bf16 v[116:119], v[152:155], v[214:217], v[116:119]
	v_mfma_f32_16x16x32_bf16 v[34:37], v[170:173], v[214:217], v[34:37]
	v_mfma_f32_16x16x32_bf16 v[136:139], v[156:159], v[188:191], v[136:139]
	v_mfma_f32_16x16x32_bf16 v[62:65], v[174:177], v[188:191], v[62:65]
	v_mfma_f32_16x16x32_bf16 v[128:131], v[156:159], v[196:199], v[128:131]
	v_mfma_f32_16x16x32_bf16 v[48:51], v[174:177], v[196:199], v[46:49]
	v_mfma_f32_16x16x32_bf16 v[120:123], v[156:159], v[204:207], v[120:123]
	v_mfma_f32_16x16x32_bf16 v[38:41], v[174:177], v[204:207], v[38:41]
	v_mfma_f32_16x16x32_bf16 v[116:119], v[156:159], v[218:221], v[116:119]
	v_mfma_f32_16x16x32_bf16 v[34:37], v[174:177], v[218:221], v[34:37]
	s_setprio 0
	s_barrier
	s_add_i32 s45, s45, s4
	v_lshl_add_u64 v[182:183], s[48:49], 0, v[184:185]
	s_mov_b32 m0, s45
	ds_read_b128 v[178:181], v213 offset:16384
	ds_read_b128 v[188:191], v213 offset:17408
	ds_read_b128 v[192:195], v213 offset:18432
	ds_read_b128 v[196:199], v213 offset:19456
	ds_read_b128 v[200:203], v213 offset:20480
	ds_read_b128 v[204:207], v213 offset:21504
	ds_read_b128 v[214:217], v213 offset:22528
	ds_read_b128 v[218:221], v213 offset:23552
	global_load_lds_dwordx4 v[182:183], off
	s_add_i32 m0, s45, 0x2000
	v_lshl_add_u64 v[208:209], s[48:49], 0, v[160:161]
	s_add_u32 s48, s48, s16
	s_addc_u32 s49, s49, s17
	s_add_i32 s41, s41, s4
	global_load_lds_dwordx4 v[208:209], off
	v_lshl_add_u64 v[222:223], s[48:49], 0, v[184:185]
	s_mov_b32 m0, s41
	v_lshl_add_u64 v[224:225], s[48:49], 0, v[160:161]
	global_load_lds_dwordx4 v[222:223], off
	s_add_i32 m0, s41, 0x2000
	v_lshl_add_u64 v[226:227], s[38:39], 0, v[164:165]
	global_load_lds_dwordx4 v[224:225], off
	s_mov_b32 m0, s82
	v_lshl_add_u64 v[228:229], s[38:39], 0, v[162:163]
	global_load_lds_dwordx4 v[226:227], off
	s_mov_b32 m0, s95
	s_nop 0
	global_load_lds_dwordx4 v[228:229], off
	s_waitcnt vmcnt(8)
	s_waitcnt lgkmcnt(0)
	s_barrier
; #define PG8_STAGE(bufoff, gbase, voff) do { _Pragma("unroll") for (int _i = 0; _i < 2; ++_i) \
;         __builtin_amdgcn_global_load_lds((const unsigned*)((const char*)(gbase) + (voff)[_i]), (LAS unsigned*)(lds + (bufoff) + ldsw + _i * 8192), 16, 0, 0); } while (0)
; #define PG8_LDA(dst, b, h) do { _Pragma("unroll") for (int m = 0; m < 4; ++m) _Pragma("unroll") for (int k = 0; k < 2; ++k) dst[m][k] = *(const LAS bf16x8*)(lds + PG8_SA(b, h) + aoff + m * 2048 + k * 1024); } while (0)
; #define PG8_LDB(dst, b, h) do { _Pragma("unroll") for (int n = 0; n < 2; ++n) _Pragma("unroll") for (int k = 0; k < 2; ++k) dst[n][k] = *(const LAS bf16x8*)(lds + PG8_SB(b, h) + boff + n * 2048 + k * 1024); } while (0)
; #define PG8_MMA(ai, bj, At, Bt) do { __builtin_amdgcn_s_setprio(1); _Pragma("unroll") for (int m = 0; m < 4; ++m) _Pragma("unroll") for (int n = 0; n < 2; ++n) _Pragma("unroll") for (int k = 0; k < 2; ++k) \
;         acc[ai][bj][m][n] = __builtin_amdgcn_mfma_f32_16x16x32_bf16(Bt[n][k], At[m][k], acc[ai][bj][m][n], 0, 0, 0); __builtin_amdgcn_s_setprio(0); } while (0)
; #define PG8_WAIT_V(n) asm volatile("s_waitcnt vmcnt(" #n ")" ::: "memory")
; #define PG8_WAIT_L(n) asm volatile("s_waitcnt lgkmcnt(" #n ")" ::: "memory")
; #define PG8_BAR __builtin_amdgcn_s_barrier()
; #define PG8_SCHED __builtin_amdgcn_sched_barrier(0)
; template <class Epi, bool ALIGN_EPI>
; __device__ __forceinline__ void gemm_phase(LAS unsigned char* lds, const Gemm g, const StaticOrder& S, const Epi& E, const int wave_s) {
;     ...
;             PG8_WAIT_V(8); PG8_WAIT_L(0); PG8_BAR; PG8_MMA(1, 0, At, B0); PG8_MMA(1, 1, At, B1); PG8_BAR; PG8_SCHED;
;             PG8_LDB(B0, 1, 0); PG8_LDB(B1, 1, 1); PG8_SCHED; PG8_LDA(At, 1, 0); PG8_STAGE(PG8_SA(0, 1), a2 + hstepA, voffA);
;             PG8_WAIT_V(8); PG8_WAIT_L(0); PG8_BAR; PG8_MMA(0, 0, At, B0); PG8_MMA(0, 1, At, B1); PG8_BAR; PG8_SCHED;
	s_setprio 1
	s_waitcnt lgkmcnt(0)
	v_mfma_f32_16x16x32_bf16 v[112:115], v[96:99], v[178:181], v[112:115]
	v_mfma_f32_16x16x32_bf16 v[30:33], v[104:107], v[178:181], v[30:33]
	v_mfma_f32_16x16x32_bf16 v[108:111], v[96:99], v[192:195], v[108:111]
	v_mfma_f32_16x16x32_bf16 v[26:29], v[104:107], v[192:195], v[26:29]
	v_mfma_f32_16x16x32_bf16 v[88:91], v[96:99], v[200:203], v[88:91]
	v_mfma_f32_16x16x32_bf16 v[16:19], v[104:107], v[200:203], v[16:19]
	v_mfma_f32_16x16x32_bf16 v[78:81], v[96:99], v[214:217], v[80:83]
	v_mfma_f32_16x16x32_bf16 v[8:11], v[104:107], v[214:217], v[8:11]
	v_mfma_f32_16x16x32_bf16 v[112:115], v[100:103], v[188:191], v[112:115]
	v_mfma_f32_16x16x32_bf16 v[30:33], v[140:143], v[188:191], v[30:33]
	v_mfma_f32_16x16x32_bf16 v[108:111], v[100:103], v[196:199], v[108:111]
	v_mfma_f32_16x16x32_bf16 v[26:29], v[140:143], v[196:199], v[26:29]
	v_mfma_f32_16x16x32_bf16 v[88:91], v[100:103], v[204:207], v[88:91]
	v_mfma_f32_16x16x32_bf16 v[16:19], v[140:143], v[204:207], v[16:19]
	v_mfma_f32_16x16x32_bf16 v[78:81], v[100:103], v[218:221], v[78:81]
	v_mfma_f32_16x16x32_bf16 v[8:11], v[140:143], v[218:221], v[8:11]
	s_setprio 0
	s_setprio 1
	v_mfma_f32_16x16x32_bf16 v[92:95], v[152:155], v[178:181], v[92:95]
	v_mfma_f32_16x16x32_bf16 v[20:23], v[170:173], v[178:181], v[22:25]
	v_mfma_f32_16x16x32_bf16 v[82:85], v[152:155], v[192:195], v[84:87]
	v_mfma_f32_16x16x32_bf16 v[12:15], v[170:173], v[192:195], v[12:15]
	v_mfma_f32_16x16x32_bf16 v[74:77], v[152:155], v[200:203], v[74:77]
	v_mfma_f32_16x16x32_bf16 v[4:7], v[170:173], v[200:203], v[4:7]
	v_mfma_f32_16x16x32_bf16 v[70:73], v[152:155], v[214:217], v[70:73]
	v_mfma_f32_16x16x32_bf16 v[0:3], v[170:173], v[214:217], v[0:3]
	v_mfma_f32_16x16x32_bf16 v[92:95], v[156:159], v[188:191], v[92:95]
	v_mfma_f32_16x16x32_bf16 v[20:23], v[174:177], v[188:191], v[20:23]
	v_mfma_f32_16x16x32_bf16 v[84:87], v[156:159], v[196:199], v[82:85]
	v_mfma_f32_16x16x32_bf16 v[12:15], v[174:177], v[196:199], v[12:15]
	v_mfma_f32_16x16x32_bf16 v[74:77], v[156:159], v[204:207], v[74:77]
	v_mfma_f32_16x16x32_bf16 v[4:7], v[174:177], v[204:207], v[4:7]
	v_mfma_f32_16x16x32_bf16 v[70:73], v[156:159], v[218:221], v[70:73]
	v_mfma_f32_16x16x32_bf16 v[0:3], v[174:177], v[218:221], v[0:3]
	s_setprio 0
	s_barrier
	s_add_i32 s41, 0, 0x18000
	v_add_u32_e32 v24, s41, v212
	s_add_i32 s45, 0, 0x1c000
	ds_read_b128 v[96:99], v24
	ds_read_b128 v[100:103], v24 offset:1024
	ds_read_b128 v[104:107], v24 offset:2048
	ds_read_b128 v[140:143], v24 offset:3072
	v_add_u32_e32 v24, s45, v212
	ds_read_b128 v[152:155], v24
	ds_read_b128 v[156:159], v24 offset:1024
	ds_read_b128 v[170:173], v24 offset:2048
	ds_read_b128 v[174:177], v24 offset:3072
	s_add_u32 s38, s38, s14
	s_addc_u32 s39, s39, s15
	s_mov_b32 m0, s87
	ds_read_b128 v[178:181], v213 offset:32768
	ds_read_b128 v[188:191], v213 offset:33792
	ds_read_b128 v[192:195], v213 offset:34816
	ds_read_b128 v[196:199], v213 offset:35840
	ds_read_b128 v[200:203], v213 offset:36864
	ds_read_b128 v[204:207], v213 offset:37888
	ds_read_b128 v[214:217], v213 offset:38912
	ds_read_b128 v[218:221], v213 offset:39936
	global_load_lds_dwordx4 v164, s[38:39]
	s_mov_b32 m0, s24
	s_nop 0
	global_load_lds_dwordx4 v162, s[38:39]
	s_waitcnt vmcnt(8)
	s_waitcnt lgkmcnt(0)
	s_barrier
	s_setprio 1
	s_waitcnt lgkmcnt(0)
	v_mfma_f32_16x16x32_bf16 v[148:151], v[96:99], v[178:181], v[148:151]
	v_mfma_f32_16x16x32_bf16 v[52:55], v[104:107], v[178:181], v[52:55]
	v_mfma_f32_16x16x32_bf16 v[144:147], v[96:99], v[192:195], v[144:147]
	v_mfma_f32_16x16x32_bf16 v[66:69], v[104:107], v[192:195], v[66:69]
	v_mfma_f32_16x16x32_bf16 v[132:135], v[96:99], v[200:203], v[132:135]
	v_mfma_f32_16x16x32_bf16 v[58:61], v[104:107], v[200:203], v[58:61]
	v_mfma_f32_16x16x32_bf16 v[124:127], v[96:99], v[214:217], v[124:127]
	v_mfma_f32_16x16x32_bf16 v[42:45], v[104:107], v[214:217], v[42:45]
	v_mfma_f32_16x16x32_bf16 v[148:151], v[100:103], v[188:191], v[148:151]
	v_mfma_f32_16x16x32_bf16 v[54:57], v[140:143], v[188:191], v[52:55]
	v_mfma_f32_16x16x32_bf16 v[144:147], v[100:103], v[196:199], v[144:147]
	v_mfma_f32_16x16x32_bf16 v[66:69], v[140:143], v[196:199], v[66:69]
	v_mfma_f32_16x16x32_bf16 v[132:135], v[100:103], v[204:207], v[132:135]
	v_mfma_f32_16x16x32_bf16 v[58:61], v[140:143], v[204:207], v[58:61]
	v_mfma_f32_16x16x32_bf16 v[124:127], v[100:103], v[218:221], v[124:127]
	v_mfma_f32_16x16x32_bf16 v[44:47], v[140:143], v[218:221], v[42:45]
	s_setprio 0
	s_setprio 1
	v_mfma_f32_16x16x32_bf16 v[136:139], v[152:155], v[178:181], v[136:139]
	v_mfma_f32_16x16x32_bf16 v[62:65], v[170:173], v[178:181], v[62:65]
	v_mfma_f32_16x16x32_bf16 v[128:131], v[152:155], v[192:195], v[128:131]
	v_mfma_f32_16x16x32_bf16 v[48:51], v[170:173], v[192:195], v[48:51]
	v_mfma_f32_16x16x32_bf16 v[120:123], v[152:155], v[200:203], v[120:123]
	v_mfma_f32_16x16x32_bf16 v[38:41], v[170:173], v[200:203], v[38:41]
	v_mfma_f32_16x16x32_bf16 v[116:119], v[152:155], v[214:217], v[116:119]
	v_mfma_f32_16x16x32_bf16 v[34:37], v[170:173], v[214:217], v[34:37]
	v_mfma_f32_16x16x32_bf16 v[136:139], v[156:159], v[188:191], v[136:139]
	v_mfma_f32_16x16x32_bf16 v[62:65], v[174:177], v[188:191], v[62:65]
	v_mfma_f32_16x16x32_bf16 v[128:131], v[156:159], v[196:199], v[128:131]
	v_mfma_f32_16x16x32_bf16 v[48:51], v[174:177], v[196:199], v[48:51]
	v_mfma_f32_16x16x32_bf16 v[120:123], v[156:159], v[204:207], v[120:123]
	v_mfma_f32_16x16x32_bf16 v[38:41], v[174:177], v[204:207], v[38:41]
	v_mfma_f32_16x16x32_bf16 v[116:119], v[156:159], v[218:221], v[116:119]
	v_mfma_f32_16x16x32_bf16 v[34:37], v[174:177], v[218:221], v[34:37]
	s_setprio 0
	s_barrier
; #define PG8_STAGE(bufoff, gbase, voff) do { _Pragma("unroll") for (int _i = 0; _i < 2; ++_i) \
;         __builtin_amdgcn_global_load_lds((const unsigned*)((const char*)(gbase) + (voff)[_i]), (LAS unsigned*)(lds + (bufoff) + ldsw + _i * 8192), 16, 0, 0); } while (0)
; #define PG8_LDA(dst, b, h) do { _Pragma("unroll") for (int m = 0; m < 4; ++m) _Pragma("unroll") for (int k = 0; k < 2; ++k) dst[m][k] = *(const LAS bf16x8*)(lds + PG8_SA(b, h) + aoff + m * 2048 + k * 1024); } while (0)
; #define PG8_MMA(ai, bj, At, Bt) do { __builtin_amdgcn_s_setprio(1); _Pragma("unroll") for (int m = 0; m < 4; ++m) _Pragma("unroll") for (int n = 0; n < 2; ++n) _Pragma("unroll") for (int k = 0; k < 2; ++k) \
;         acc[ai][bj][m][n] = __builtin_amdgcn_mfma_f32_16x16x32_bf16(Bt[n][k], At[m][k], acc[ai][bj][m][n], 0, 0, 0); __builtin_amdgcn_s_setprio(0); } while (0)
; #define PG8_WAIT_V(n) asm volatile("s_waitcnt vmcnt(" #n ")" ::: "memory")
; #define PG8_WAIT_L(n) asm volatile("s_waitcnt lgkmcnt(" #n ")" ::: "memory")
; #define PG8_BAR __builtin_amdgcn_s_barrier()
; #define PG8_SCHED __builtin_amdgcn_sched_barrier(0)
; template <class Epi, bool ALIGN_EPI>
; __device__ __forceinline__ void gemm_phase(LAS unsigned char* lds, const Gemm g, const StaticOrder& S, const Epi& E, const int wave_s) {
;     ...
;             PG8_LDA(At, 1, 1); PG8_STAGE(PG8_SB(1, 0), b3, voffB); PG8_STAGE(PG8_SB(1, 1), b3 + hstepB, voffB); PG8_STAGE(PG8_SA(1, 0), a3, voffA);
;             PG8_WAIT_V(8); PG8_WAIT_L(0); PG8_BAR; PG8_MMA(1, 0, At, B0); PG8_MMA(1, 1, At, B1); PG8_BAR; PG8_SCHED;
;         }
	s_add_i32 s38, s41, s4
	v_lshl_add_u64 v[24:25], v[182:183], 0, s[64:65]
	s_mov_b32 m0, s38
	ds_read_b128 v[178:181], v213 offset:49152
	ds_read_b128 v[188:191], v213 offset:50176
	ds_read_b128 v[192:195], v213 offset:51200
	ds_read_b128 v[196:199], v213 offset:52224
	ds_read_b128 v[200:203], v213 offset:53248
	ds_read_b128 v[204:207], v213 offset:54272
	ds_read_b128 v[214:217], v213 offset:55296
	ds_read_b128 v[218:221], v213 offset:56320
	global_load_lds_dwordx4 v[24:25], off
	v_lshl_add_u64 v[24:25], v[208:209], 0, s[64:65]
	s_add_i32 m0, s38, 0x2000
	s_add_i32 s38, s45, s4
	global_load_lds_dwordx4 v[24:25], off
	v_lshl_add_u64 v[24:25], v[222:223], 0, s[64:65]
	s_mov_b32 m0, s38
	s_nop 0
	global_load_lds_dwordx4 v[24:25], off
	v_lshl_add_u64 v[24:25], v[224:225], 0, s[64:65]
	s_add_i32 m0, s38, 0x2000
	s_nop 0
	global_load_lds_dwordx4 v[24:25], off
	v_lshl_add_u64 v[24:25], v[226:227], 0, s[64:65]
	s_mov_b32 m0, s25
	s_nop 0
	global_load_lds_dwordx4 v[24:25], off
	v_lshl_add_u64 v[24:25], v[228:229], 0, s[64:65]
	s_mov_b32 m0, s86
	s_nop 0
	global_load_lds_dwordx4 v[24:25], off
	s_waitcnt vmcnt(8)
	s_waitcnt lgkmcnt(0)
	s_barrier
	s_setprio 1
	s_waitcnt lgkmcnt(0)
	v_mfma_f32_16x16x32_bf16 v[112:115], v[96:99], v[178:181], v[112:115]
	v_mfma_f32_16x16x32_bf16 v[30:33], v[104:107], v[178:181], v[30:33]
	v_mfma_f32_16x16x32_bf16 v[108:111], v[96:99], v[192:195], v[108:111]
	v_mfma_f32_16x16x32_bf16 v[24:27], v[104:107], v[192:195], v[26:29]
	v_mfma_f32_16x16x32_bf16 v[88:91], v[96:99], v[200:203], v[88:91]
	v_mfma_f32_16x16x32_bf16 v[16:19], v[104:107], v[200:203], v[16:19]
	v_mfma_f32_16x16x32_bf16 v[78:81], v[96:99], v[214:217], v[78:81]
	v_mfma_f32_16x16x32_bf16 v[8:11], v[104:107], v[214:217], v[8:11]
	v_mfma_f32_16x16x32_bf16 v[112:115], v[100:103], v[188:191], v[112:115]
	v_mfma_f32_16x16x32_bf16 v[30:33], v[140:143], v[188:191], v[30:33]
	v_mfma_f32_16x16x32_bf16 v[108:111], v[100:103], v[196:199], v[108:111]
	v_mfma_f32_16x16x32_bf16 v[26:29], v[140:143], v[196:199], v[24:27]
	v_mfma_f32_16x16x32_bf16 v[88:91], v[100:103], v[204:207], v[88:91]
	v_mfma_f32_16x16x32_bf16 v[16:19], v[140:143], v[204:207], v[16:19]
	v_mfma_f32_16x16x32_bf16 v[80:83], v[100:103], v[218:221], v[78:81]
	v_mfma_f32_16x16x32_bf16 v[8:11], v[140:143], v[218:221], v[8:11]
	s_setprio 0
	s_setprio 1
	v_mfma_f32_16x16x32_bf16 v[92:95], v[152:155], v[178:181], v[92:95]
	v_mfma_f32_16x16x32_bf16 v[20:23], v[170:173], v[178:181], v[20:23]
	v_mfma_f32_16x16x32_bf16 v[84:87], v[152:155], v[192:195], v[84:87]
	v_mfma_f32_16x16x32_bf16 v[12:15], v[170:173], v[192:195], v[12:15]
	v_mfma_f32_16x16x32_bf16 v[74:77], v[152:155], v[200:203], v[74:77]
	v_mfma_f32_16x16x32_bf16 v[4:7], v[170:173], v[200:203], v[4:7]
	v_mfma_f32_16x16x32_bf16 v[70:73], v[152:155], v[214:217], v[70:73]
	v_mfma_f32_16x16x32_bf16 v[0:3], v[170:173], v[214:217], v[0:3]
	v_mfma_f32_16x16x32_bf16 v[92:95], v[156:159], v[188:191], v[92:95]
	v_mfma_f32_16x16x32_bf16 v[22:25], v[174:177], v[188:191], v[20:23]
	v_mfma_f32_16x16x32_bf16 v[84:87], v[156:159], v[196:199], v[84:87]
	v_mfma_f32_16x16x32_bf16 v[12:15], v[174:177], v[196:199], v[12:15]
	v_mfma_f32_16x16x32_bf16 v[74:77], v[156:159], v[204:207], v[74:77]
	v_mfma_f32_16x16x32_bf16 v[4:7], v[174:177], v[204:207], v[4:7]
	v_mfma_f32_16x16x32_bf16 v[70:73], v[156:159], v[218:221], v[70:73]
	v_mfma_f32_16x16x32_bf16 v[0:3], v[174:177], v[218:221], v[0:3]
	s_setprio 0
	s_barrier
	s_add_u32 s43, s43, 0x100
	s_addc_u32 s44, s44, 0
	s_add_u32 s0, s0, 0x100
	s_addc_u32 s1, s1, 0
	s_cmp_ge_i32 s40, s63
	s_mov_b32 s38, s40
	s_cbranch_scc0 .LBB0_180
	s_branch .LBB0_182
